# diff-attention tile loop: scale folded into exp argument via pk_fma (no separate scale pass), V fragments double-buffered per 16-key pack, row-sum interleaved with PV MFMAs
# speedup vs baseline: 1.0032x; 1.0020x over previous
; #define LAS __attribute__((address_space(3)))
; #define MFMA32(a, b, c) __builtin_amdgcn_mfma_f32_32x32x16_bf16((a), (b), (c), 0, 0, 0)
; template <int KSTEPS, class Pol>
; __device__ __forceinline__ void attn_pass(LAS unsigned char* lds, const Pol& P, const bf16_t* qb, int ldq, const bf16_t* kb, int ldk, const bf16_t* vb, int ldv,
;                                           float qs, f32x16 (&O)[4], float& m, float& l) {
;     ...
;     auto qk_softmax = [&](int st, int t) __attribute__((always_inline)) {
;         LAS unsigned char* Kb = lds + st * A_STAGE + krow;
;         f32x16 S0, S1;
;         P.fill(S0, S1, qi, half, t, wave);
; #pragma unroll
;         for (int ks = 0; ks < KSTEPS; ++ks) {
;             const int so = ((2 * ks) ^ kx) << 4;
;             const bf16x8 a0 = *(const LAS bf16x8*)(Kb + so);
;             const bf16x8 a1 = *(const LAS bf16x8*)(Kb + 32 * KROWB + so);
;             S0 = MFMA32(a0, qf[ks], S0);
;             S1 = MFMA32(a1, qf[ks], S1);
;         }
;         S0 = S0 * qs; S1 = S1 * qs;
;         float mx = fmaxf(S0[0], S1[0]);
; #pragma unroll
;         for (int i = 1; i < 16; ++i) mx = fmaxf(fmaxf(mx, S0[i]), S1[i]);
;         mx = fmaxf(mx, __shfl_xor(mx, 32));
;         const float mnew = fmaxf(m, mx);
;         const float alpha = __builtin_amdgcn_exp2f(m - mnew);
;         m = mnew;
.LBB0_505:
	s_add_i32 s36, s51, 0
	v_add_u32_e32 v0, s36, v151
	v_add_u32_e32 v6, v0, v152
	ds_read_b128 v[2:5], v6
	ds_read_b128 v[6:9], v6 offset:4096
	v_add_u32_e32 v200, v0, v153
	ds_read_b128 v[192:195], v200
	ds_read_b128 v[196:199], v200 offset:4096
	s_mov_b32 s40, 0x3e38aa3b
	s_waitcnt lgkmcnt(3)
	v_mfma_f32_32x32x16_bf16 v[80:95], v[2:5], v[112:115], v[80:95]
	s_waitcnt lgkmcnt(2)
	v_mfma_f32_32x32x16_bf16 v[96:111], v[6:9], v[112:115], v[96:111]
	v_add_u32_e32 v6, v0, v155
	ds_read_b128 v[2:5], v6
	ds_read_b128 v[6:9], v6 offset:4096
	s_waitcnt lgkmcnt(3)
	v_mfma_f32_32x32x16_bf16 v[80:95], v[192:195], v[116:119], v[80:95]
	s_waitcnt lgkmcnt(2)
	v_mfma_f32_32x32x16_bf16 v[96:111], v[196:199], v[116:119], v[96:111]
	v_add_u32_e32 v200, v0, v156
	ds_read_b128 v[192:195], v200
	ds_read_b128 v[196:199], v200 offset:4096
	s_waitcnt lgkmcnt(3)
	v_mfma_f32_32x32x16_bf16 v[80:95], v[2:5], v[120:123], v[80:95]
	s_waitcnt lgkmcnt(2)
	v_mfma_f32_32x32x16_bf16 v[96:111], v[6:9], v[120:123], v[96:111]
	s_waitcnt lgkmcnt(1)
	v_mfma_f32_32x32x16_bf16 v[80:95], v[192:195], v[124:127], v[80:95]
	s_waitcnt lgkmcnt(0)
	v_mfma_f32_32x32x16_bf16 v[96:111], v[196:199], v[124:127], v[96:111]
	v_add_u32_e32 v7, s36, v158
	v_add_u32_e32 v139, s36, v159
	v_add_u32_e32 v142, s36, v160
	v_add_u32_e32 v143, s36, v161
	v_add_u32_e32 v146, s36, v162
	v_add_u32_e32 v147, s36, v163
	v_add_u32_e32 v169, s36, v164
	v_add_u32_e32 v170, s36, v165
	ds_read_b64_tr_b16 v[176:177], v7 offset:16384
	ds_read_b64_tr_b16 v[178:179], v139 offset:2048
	ds_read_b64_tr_b16 v[180:181], v142 offset:16384
	ds_read_b64_tr_b16 v[182:183], v143 offset:2048
	ds_read_b64_tr_b16 v[192:193], v146 offset:16384
	ds_read_b64_tr_b16 v[194:195], v147 offset:2048
	ds_read_b64_tr_b16 v[196:197], v169 offset:16384
	ds_read_b64_tr_b16 v[198:199], v170 offset:2048
	v_max_f32_e32 v0, v80, v96
	v_max3_f32 v0, v0, v81, v97
	v_max3_f32 v0, v0, v82, v98
	v_max3_f32 v0, v0, v83, v99
	v_max3_f32 v0, v0, v84, v100
	v_max3_f32 v0, v0, v85, v101
	v_max3_f32 v0, v0, v86, v102
	v_max3_f32 v0, v0, v87, v103
	v_max3_f32 v0, v0, v88, v104
	v_max3_f32 v0, v0, v89, v105
	v_max3_f32 v0, v0, v90, v106
	v_max3_f32 v0, v0, v91, v107
	v_max3_f32 v0, v0, v92, v108
	v_max3_f32 v0, v0, v93, v109
	v_max3_f32 v0, v0, v94, v110
	v_max3_f32 v0, v0, v95, v111
	v_mul_f32_e64 v0, v0, s40
	ds_bpermute_b32 v6, v148, v0
	s_waitcnt lgkmcnt(0)
	v_max3_f32 v0, v167, v0, v6
	v_sub_f32_e32 v6, v167, v0
	v_exp_f32_e32 v6, v6
	s_nop 0
	v_cmp_neq_f32_e32 vcc, 1.0, v6
	s_cbranch_vccz .LBB0_507
	v_pk_mul_f32 v[78:79], v[78:79], v[6:7] op_sel_hi:[1,0]
	v_pk_mul_f32 v[76:77], v[76:77], v[6:7] op_sel_hi:[1,0]
	v_pk_mul_f32 v[74:75], v[74:75], v[6:7] op_sel_hi:[1,0]
	v_pk_mul_f32 v[72:73], v[72:73], v[6:7] op_sel_hi:[1,0]
	v_pk_mul_f32 v[70:71], v[70:71], v[6:7] op_sel_hi:[1,0]
	v_pk_mul_f32 v[68:69], v[68:69], v[6:7] op_sel_hi:[1,0]
	v_pk_mul_f32 v[66:67], v[66:67], v[6:7] op_sel_hi:[1,0]
	v_pk_mul_f32 v[64:65], v[64:65], v[6:7] op_sel_hi:[1,0]
	v_pk_mul_f32 v[62:63], v[62:63], v[6:7] op_sel_hi:[1,0]
	v_pk_mul_f32 v[60:61], v[60:61], v[6:7] op_sel_hi:[1,0]
	v_pk_mul_f32 v[58:59], v[58:59], v[6:7] op_sel_hi:[1,0]
	v_pk_mul_f32 v[56:57], v[56:57], v[6:7] op_sel_hi:[1,0]
	v_pk_mul_f32 v[54:55], v[54:55], v[6:7] op_sel_hi:[1,0]
	v_pk_mul_f32 v[52:53], v[52:53], v[6:7] op_sel_hi:[1,0]
	v_pk_mul_f32 v[50:51], v[50:51], v[6:7] op_sel_hi:[1,0]
	v_pk_mul_f32 v[48:49], v[48:49], v[6:7] op_sel_hi:[1,0]
	v_pk_mul_f32 v[46:47], v[46:47], v[6:7] op_sel_hi:[1,0]
	v_pk_mul_f32 v[44:45], v[44:45], v[6:7] op_sel_hi:[1,0]
	v_pk_mul_f32 v[42:43], v[42:43], v[6:7] op_sel_hi:[1,0]
	v_pk_mul_f32 v[40:41], v[40:41], v[6:7] op_sel_hi:[1,0]
	v_pk_mul_f32 v[38:39], v[38:39], v[6:7] op_sel_hi:[1,0]
	v_pk_mul_f32 v[36:37], v[36:37], v[6:7] op_sel_hi:[1,0]
	v_pk_mul_f32 v[34:35], v[34:35], v[6:7] op_sel_hi:[1,0]
	v_pk_mul_f32 v[32:33], v[32:33], v[6:7] op_sel_hi:[1,0]
	v_pk_mul_f32 v[30:31], v[30:31], v[6:7] op_sel_hi:[1,0]
	v_pk_mul_f32 v[28:29], v[28:29], v[6:7] op_sel_hi:[1,0]
	v_pk_mul_f32 v[26:27], v[26:27], v[6:7] op_sel_hi:[1,0]
	v_pk_mul_f32 v[24:25], v[24:25], v[6:7] op_sel_hi:[1,0]
	v_pk_mul_f32 v[22:23], v[22:23], v[6:7] op_sel_hi:[1,0]
	v_pk_mul_f32 v[20:21], v[20:21], v[6:7] op_sel_hi:[1,0]
	v_pk_mul_f32 v[18:19], v[18:19], v[6:7] op_sel_hi:[1,0]
	v_pk_mul_f32 v[16:17], v[16:17], v[6:7] op_sel_hi:[1,0]
; #define LAS __attribute__((address_space(3)))
; __device__ __forceinline__ unsigned pk2(float lo, float hi) { f32x2 v = {lo, hi}; bf16x2_t b = __builtin_convertvector(v, bf16x2_t); return __builtin_bit_cast(unsigned, b); }
; #define MFMA32(a, b, c) __builtin_amdgcn_mfma_f32_32x32x16_bf16((a), (b), (c), 0, 0, 0)
; template <int KSTEPS, class Pol>
; __device__ __forceinline__ void attn_pass(LAS unsigned char* lds, const Pol& P, const bf16_t* qb, int ldq, const bf16_t* kb, int ldk, const bf16_t* vb, int ldv,
;                                           float qs, f32x16 (&O)[4], float& m, float& l) {
;     ...
;             const f32x2 nm = {-mnew, -mnew};
; #pragma unroll
;             for (int i = 0; i < 16; i += 2) { const f32x2 a = (f32x2){S0[i], S0[i + 1]} + nm, b = (f32x2){S1[i], S1[i + 1]} + nm; S0[i] = a.x; S0[i + 1] = a.y; S1[i] = b.x; S1[i + 1] = b.y; }
;         }
;         f32x2 ls2 = {0.f, 0.f};
; #pragma unroll
;         for (int s = 0; s < 4; ++s) {
;             unsigned w[4];
; #pragma unroll
;             for (int e = 0; e < 4; ++e) {
;                 const int i = 8 * (s & 1) + 2 * e;
;                 f32x2 pv;
;                 pv.x = __builtin_amdgcn_exp2f(s < 2 ? S0[i] : S1[i]); pv.y = __builtin_amdgcn_exp2f(s < 2 ? S0[i + 1] : S1[i + 1]);
;                 ls2 = ls2 + pv;
;                 w[e] = pk2(pv.x, pv.y);
;             }
;             u32x4 wv; wv.x = w[0]; wv.y = w[1]; wv.z = w[2]; wv.w = w[3];
;             pf[s] = __builtin_bit_cast(bf16x8, wv);
;         }
;         l = l * alpha + (ls2.x + ls2.y);
;         if (__any(alpha != 1.0f)) {
; #pragma unroll
;             for (int blk = 0; blk < 4; ++blk) O[blk] = O[blk] * alpha;
;         }
;     };
;     auto pv_acc = [&](int st) __attribute__((always_inline)) {
;         LAS unsigned char* Vb = lds + st * A_STAGE;
; #pragma unroll
;         for (int s = 0; s < 4; ++s) {
; #pragma unroll
;             for (int blk = 0; blk < 4; ++blk) {
;                 const s16x4 lo = __builtin_amdgcn_ds_read_tr16_b64_v4i16((LAS s16x4*)(Vb + s * 4096 + voffs[blk][0]));
;                 const s16x4 hi = __builtin_amdgcn_ds_read_tr16_b64_v4i16((LAS s16x4*)(Vb + s * 4096 + voffs[blk][1]));
;                 const bf16x8 va = __builtin_shufflevector(lo, hi, 0, 1, 2, 3, 4, 5, 6, 7);
;                 O[blk] = MFMA32(va, pf[s], O[blk]);
;             }
;         }
.LBB0_507:
	ds_read_b64_tr_b16 v[216:217], v7 offset:20480
	ds_read_b64_tr_b16 v[218:219], v139 offset:6144
	ds_read_b64_tr_b16 v[220:221], v142 offset:20480
	ds_read_b64_tr_b16 v[222:223], v143 offset:6144
	ds_read_b64_tr_b16 v[224:225], v146 offset:20480
	ds_read_b64_tr_b16 v[226:227], v147 offset:6144
	ds_read_b64_tr_b16 v[228:229], v169 offset:20480
	ds_read_b64_tr_b16 v[230:231], v170 offset:6144
	v_pk_fma_f32 v[80:81], v[80:81], s[40:41], v[0:1] op_sel_hi:[1,0,0] neg_lo:[0,0,1] neg_hi:[0,0,1]
	v_pk_fma_f32 v[82:83], v[82:83], s[40:41], v[0:1] op_sel_hi:[1,0,0] neg_lo:[0,0,1] neg_hi:[0,0,1]
	v_pk_fma_f32 v[84:85], v[84:85], s[40:41], v[0:1] op_sel_hi:[1,0,0] neg_lo:[0,0,1] neg_hi:[0,0,1]
	v_pk_fma_f32 v[86:87], v[86:87], s[40:41], v[0:1] op_sel_hi:[1,0,0] neg_lo:[0,0,1] neg_hi:[0,0,1]
	v_exp_f32_e32 v80, v80
	v_exp_f32_e32 v81, v81
	v_exp_f32_e32 v82, v82
	v_exp_f32_e32 v83, v83
	v_exp_f32_e32 v84, v84
	v_exp_f32_e32 v85, v85
	v_exp_f32_e32 v86, v86
	v_exp_f32_e32 v87, v87
	v_pk_fma_f32 v[88:89], v[88:89], s[40:41], v[0:1] op_sel_hi:[1,0,0] neg_lo:[0,0,1] neg_hi:[0,0,1]
	v_pk_fma_f32 v[90:91], v[90:91], s[40:41], v[0:1] op_sel_hi:[1,0,0] neg_lo:[0,0,1] neg_hi:[0,0,1]
	v_cvt_pk_bf16_f32 v208, v80, v81
	v_cvt_pk_bf16_f32 v209, v82, v83
	v_cvt_pk_bf16_f32 v210, v84, v85
	v_cvt_pk_bf16_f32 v211, v86, v87
	v_pk_fma_f32 v[92:93], v[92:93], s[40:41], v[0:1] op_sel_hi:[1,0,0] neg_lo:[0,0,1] neg_hi:[0,0,1]
	v_pk_fma_f32 v[94:95], v[94:95], s[40:41], v[0:1] op_sel_hi:[1,0,0] neg_lo:[0,0,1] neg_hi:[0,0,1]
	v_pk_add_f32 v[204:205], v[80:81], v[82:83]
	v_mfma_f32_32x32x16_bf16 v[64:79], v[176:179], v[208:211], v[64:79]
	v_exp_f32_e32 v88, v88
	v_exp_f32_e32 v89, v89
	v_exp_f32_e32 v90, v90
	v_exp_f32_e32 v91, v91
	v_pk_add_f32 v[204:205], v[84:85], v[204:205]
	v_mfma_f32_32x32x16_bf16 v[48:63], v[180:183], v[208:211], v[48:63]
	v_exp_f32_e32 v92, v92
	v_exp_f32_e32 v93, v93
	v_exp_f32_e32 v94, v94
	v_exp_f32_e32 v95, v95
	v_pk_add_f32 v[204:205], v[86:87], v[204:205]
	v_mfma_f32_32x32x16_bf16 v[32:47], v[192:195], v[208:211], v[32:47]
	v_cvt_pk_bf16_f32 v212, v88, v89
	v_cvt_pk_bf16_f32 v213, v90, v91
	v_cvt_pk_bf16_f32 v214, v92, v93
	v_cvt_pk_bf16_f32 v215, v94, v95
	v_pk_add_f32 v[204:205], v[88:89], v[204:205]
	v_mfma_f32_32x32x16_bf16 v[16:31], v[196:199], v[208:211], v[16:31]
	ds_read_b64_tr_b16 v[176:177], v7 offset:24576
	ds_read_b64_tr_b16 v[178:179], v139 offset:10240
	ds_read_b64_tr_b16 v[180:181], v142 offset:24576
	ds_read_b64_tr_b16 v[182:183], v143 offset:10240
	ds_read_b64_tr_b16 v[192:193], v146 offset:24576
	ds_read_b64_tr_b16 v[194:195], v147 offset:10240
	ds_read_b64_tr_b16 v[196:197], v169 offset:24576
	ds_read_b64_tr_b16 v[198:199], v170 offset:10240
	v_pk_add_f32 v[204:205], v[90:91], v[204:205]
	v_pk_fma_f32 v[96:97], v[96:97], s[40:41], v[0:1] op_sel_hi:[1,0,0] neg_lo:[0,0,1] neg_hi:[0,0,1]
	v_pk_fma_f32 v[98:99], v[98:99], s[40:41], v[0:1] op_sel_hi:[1,0,0] neg_lo:[0,0,1] neg_hi:[0,0,1]
	v_pk_fma_f32 v[100:101], v[100:101], s[40:41], v[0:1] op_sel_hi:[1,0,0] neg_lo:[0,0,1] neg_hi:[0,0,1]
	v_pk_fma_f32 v[102:103], v[102:103], s[40:41], v[0:1] op_sel_hi:[1,0,0] neg_lo:[0,0,1] neg_hi:[0,0,1]
	s_waitcnt lgkmcnt(8)
	v_mfma_f32_32x32x16_bf16 v[64:79], v[216:219], v[212:215], v[64:79]
	v_exp_f32_e32 v96, v96
	v_exp_f32_e32 v97, v97
	v_exp_f32_e32 v98, v98
	v_exp_f32_e32 v99, v99
	v_pk_add_f32 v[204:205], v[92:93], v[204:205]
	v_mfma_f32_32x32x16_bf16 v[48:63], v[220:223], v[212:215], v[48:63]
	v_exp_f32_e32 v100, v100
	v_exp_f32_e32 v101, v101
	v_exp_f32_e32 v102, v102
	v_exp_f32_e32 v103, v103
	v_pk_add_f32 v[204:205], v[94:95], v[204:205]
	v_mfma_f32_32x32x16_bf16 v[32:47], v[224:227], v[212:215], v[32:47]
	v_cvt_pk_bf16_f32 v208, v96, v97
	v_cvt_pk_bf16_f32 v209, v98, v99
	v_cvt_pk_bf16_f32 v210, v100, v101
	v_cvt_pk_bf16_f32 v211, v102, v103
	v_pk_add_f32 v[204:205], v[96:97], v[204:205]
	v_mfma_f32_32x32x16_bf16 v[16:31], v[228:231], v[212:215], v[16:31]
	ds_read_b64_tr_b16 v[216:217], v7 offset:28672
	ds_read_b64_tr_b16 v[218:219], v139 offset:14336
	ds_read_b64_tr_b16 v[220:221], v142 offset:28672
	ds_read_b64_tr_b16 v[222:223], v143 offset:14336
	ds_read_b64_tr_b16 v[224:225], v146 offset:28672
	ds_read_b64_tr_b16 v[226:227], v147 offset:14336
	ds_read_b64_tr_b16 v[228:229], v169 offset:28672
	ds_read_b64_tr_b16 v[230:231], v170 offset:14336
	v_pk_add_f32 v[204:205], v[98:99], v[204:205]
	v_pk_fma_f32 v[104:105], v[104:105], s[40:41], v[0:1] op_sel_hi:[1,0,0] neg_lo:[0,0,1] neg_hi:[0,0,1]
	v_pk_fma_f32 v[106:107], v[106:107], s[40:41], v[0:1] op_sel_hi:[1,0,0] neg_lo:[0,0,1] neg_hi:[0,0,1]
	v_pk_fma_f32 v[108:109], v[108:109], s[40:41], v[0:1] op_sel_hi:[1,0,0] neg_lo:[0,0,1] neg_hi:[0,0,1]
	v_pk_fma_f32 v[110:111], v[110:111], s[40:41], v[0:1] op_sel_hi:[1,0,0] neg_lo:[0,0,1] neg_hi:[0,0,1]
	s_waitcnt lgkmcnt(8)
	v_mfma_f32_32x32x16_bf16 v[64:79], v[176:179], v[208:211], v[64:79]
	v_exp_f32_e32 v104, v104
	v_exp_f32_e32 v105, v105
	v_exp_f32_e32 v106, v106
	v_exp_f32_e32 v107, v107
	v_pk_add_f32 v[204:205], v[100:101], v[204:205]
	v_mfma_f32_32x32x16_bf16 v[48:63], v[180:183], v[208:211], v[48:63]
	v_exp_f32_e32 v108, v108
	v_exp_f32_e32 v109, v109
	v_exp_f32_e32 v110, v110
	v_exp_f32_e32 v111, v111
	v_pk_add_f32 v[204:205], v[102:103], v[204:205]
	v_mfma_f32_32x32x16_bf16 v[32:47], v[192:195], v[208:211], v[32:47]
	v_cvt_pk_bf16_f32 v212, v104, v105
	v_cvt_pk_bf16_f32 v213, v106, v107
	v_cvt_pk_bf16_f32 v214, v108, v109
	v_cvt_pk_bf16_f32 v215, v110, v111
	v_pk_add_f32 v[204:205], v[104:105], v[204:205]
	v_mfma_f32_32x32x16_bf16 v[16:31], v[196:199], v[208:211], v[16:31]
	s_add_i32 s48, s48, 1
	s_cmp_ge_i32 s48, s44
	v_pk_add_f32 v[204:205], v[106:107], v[204:205]
	s_waitcnt lgkmcnt(0)
	v_mfma_f32_32x32x16_bf16 v[64:79], v[216:219], v[212:215], v[64:79]
	v_pk_add_f32 v[204:205], v[108:109], v[204:205]
	v_mfma_f32_32x32x16_bf16 v[48:63], v[220:223], v[212:215], v[48:63]
	v_pk_add_f32 v[204:205], v[110:111], v[204:205]
	v_mfma_f32_32x32x16_bf16 v[32:47], v[224:227], v[212:215], v[32:47]
	v_mfma_f32_32x32x16_bf16 v[16:31], v[228:231], v[212:215], v[16:31]
	s_cbranch_scc1 .LBB0_513
	s_mov_b64 s[36:37], -1
	s_and_b64 vcc, exec, s[2:3]
	s_cbranch_vccz .LBB0_510
	s_waitcnt vmcnt(0)
	s_mov_b64 s[36:37], 0

; #define AWAIT(n) asm volatile("s_waitcnt vmcnt(%0)" :: "n"(n) : "memory")
; #define ABAR() asm volatile("s_waitcnt lgkmcnt(0)\n\ts_barrier" ::: "memory")
;     __device__ __forceinline__ bool wave_skip(int t, int wave) const { const int r = R + (wave >> 1), kr = kr_lo + t, a = r0(r); return kr < a || kr > a + 7; }
;     __device__ __forceinline__ bool wave_skip(int t, int wave) const { return (64 * t + 63 < 32 * wave) || (64 * t > 32 * wave + 159); }
; template <int KSTEPS, class Pol>
; __device__ __forceinline__ void attn_pass(LAS unsigned char* lds, const Pol& P, const bf16_t* qb, int ldq, const bf16_t* kb, int ldk, const bf16_t* vb, int ldv,
;                                           float qs, f32x16 (&O)[4], float& m, float& l) {
;     ...
;         l = l * alpha + (ls2.x + ls2.y);
;         if (__any(alpha != 1.0f)) {
; #pragma unroll
;             for (int blk = 0; blk < 4; ++blk) O[blk] = O[blk] * alpha;
;     ...
;     for (int t = 0; t < nt; ++t) {
;         const int st2 = (st >= 1) ? st - 1 : 2;
;         if (t + 2 < nt) dma(t + 2, st2);
;         if (!P.wave_skip(t, wave)) { qk_softmax(st, t); pv_acc(st); }
;         if (t + 1 < nt) { if (t + 2 < nt) AWAIT(NDMA); else AWAIT(0); ABAR(); }
;         st = (st == 2) ? 0 : st + 1;
.LBB0_513:
	s_add_i32 s2, s49, 1
	s_cmp_lg_u32 s49, 2
	s_cselect_b32 s49, s2, 0
	s_cmp_lg_u32 s44, s48
	v_add_f32_e32 v2, v204, v205
	v_fmac_f32_e32 v2, v166, v6
	s_cbranch_scc0 .LBB0_420
	v_mov_b32_e32 v166, v2
	v_mov_b32_e32 v167, v0
	s_branch .LBB0_497
